# B1 step 2: the b_a_log load issued together with the a/bb/dt_bias loads instead of after the softplus chain (on v028)
# baseline (speedup 1.0000x reference)
; DI float siluf(float x) { return x * __builtin_amdgcn_rcpf(1.f + __expf(-x)); }
; DI void phaseB1(const Params& p, int l, char* smem) {
;     ...
; #pragma unroll
;       for (int i8 = 0; i8 < 8; ++i8) {
;         const int i = (tid >> 5) + 8 * i8;
;         float acc[8];
; #pragma unroll
;         for (int e = 0; e < 8; ++e) acc[e] = 0.f;
; #pragma unroll
;         for (int j = 0; j < 4; ++j) {
;           const uint4 v = rw[i8][j];
;           acc[0] += wv[j][0] * __uint_as_float(v.x << 16); acc[1] += wv[j][1] * __uint_as_float(v.x & 0xffff0000u);
;           acc[2] += wv[j][2] * __uint_as_float(v.y << 16); acc[3] += wv[j][3] * __uint_as_float(v.y & 0xffff0000u);
;           acc[4] += wv[j][4] * __uint_as_float(v.z << 16); acc[5] += wv[j][5] * __uint_as_float(v.z & 0xffff0000u);
;           acc[6] += wv[j][6] * __uint_as_float(v.w << 16); acc[7] += wv[j][7] * __uint_as_float(v.w & 0xffff0000u);
;         }
;         *(float4*)(dstl + i * 132 + c0) = make_float4(siluf(acc[0]), siluf(acc[1]), siluf(acc[2]), siluf(acc[3]));
;         *(float4*)(dstl + i * 132 + c0 + 4) = make_float4(siluf(acc[4]), siluf(acc[5]), siluf(acc[6]), siluf(acc[7]));
;       }
.LBB0_1845:
	s_or_b64 exec, exec, s[8:9]
	s_waitcnt vmcnt(0)
	v_lshlrev_b32_e32 v170, 16, v150
	v_and_b32_e32 v171, 0xffff0000, v150
	v_lshlrev_b32_e32 v212, 16, v154
	v_and_b32_e32 v213, 0xffff0000, v154
	v_pk_fma_f32 v[170:171], v[18:19], v[170:171], 0 op_sel_hi:[1,1,0]
	v_lshlrev_b32_e32 v216, 16, v146
	v_and_b32_e32 v217, 0xffff0000, v146
	v_pk_fma_f32 v[170:171], v[30:31], v[212:213], v[170:171]
	v_lshlrev_b32_e32 v218, 16, v147
	v_and_b32_e32 v219, 0xffff0000, v147
	v_lshlrev_b32_e32 v146, 16, v158
	v_and_b32_e32 v147, 0xffff0000, v158
	v_pk_fma_f32 v[170:171], v[26:27], v[216:217], v[170:171]
	v_lshlrev_b32_e32 v150, 16, v151
	v_pk_fma_f32 v[146:147], v[22:23], v[146:147], v[170:171]
	v_and_b32_e32 v151, 0xffff0000, v151
	v_mul_f32_e32 v0, 0xbfb8aa3b, v146
	v_exp_f32_e32 v0, v0
	v_lshlrev_b32_e32 v154, 16, v155
	v_and_b32_e32 v155, 0xffff0000, v155
	v_pk_fma_f32 v[150:151], v[20:21], v[150:151], 0 op_sel_hi:[1,1,0]
	v_add_f32_e32 v0, 1.0, v0
	v_rcp_f32_e32 v170, v0
	v_mul_f32_e32 v0, 0xbfb8aa3b, v147
	v_exp_f32_e32 v0, v0
	v_pk_fma_f32 v[150:151], v[32:33], v[154:155], v[150:151]
	v_lshlrev_b32_e32 v220, 16, v148
	v_and_b32_e32 v221, 0xffff0000, v148
	v_lshlrev_b32_e32 v222, 16, v149
	v_and_b32_e32 v223, 0xffff0000, v149
	v_lshlrev_b32_e32 v148, 16, v159
	v_and_b32_e32 v149, 0xffff0000, v159
	v_pk_fma_f32 v[150:151], v[28:29], v[218:219], v[150:151]
	v_add_f32_e32 v0, 1.0, v0
	v_pk_fma_f32 v[148:149], v[24:25], v[148:149], v[150:151]
	v_rcp_f32_e32 v171, v0
	v_mul_f32_e32 v0, 0xbfb8aa3b, v148
	v_exp_f32_e32 v0, v0
	v_lshlrev_b32_e32 v210, 16, v152
	v_and_b32_e32 v211, 0xffff0000, v152
	v_pk_mul_f32 v[146:147], v[146:147], v[170:171]
	v_add_f32_e32 v0, 1.0, v0
	v_rcp_f32_e32 v150, v0
	v_mul_f32_e32 v0, 0xbfb8aa3b, v149
	v_exp_f32_e32 v0, v0
	v_lshlrev_b32_e32 v214, 16, v156
	v_and_b32_e32 v215, 0xffff0000, v156
	v_lshlrev_b32_e32 v158, 16, v160
	v_add_f32_e32 v0, 1.0, v0
	v_rcp_f32_e32 v151, v0
	v_and_b32_e32 v159, 0xffff0000, v160
	v_lshlrev_b32_e32 v152, 16, v153
	v_and_b32_e32 v153, 0xffff0000, v153
	v_pk_mul_f32 v[148:149], v[148:149], v[150:151]
	ds_write_b128 v207, v[146:149]
	v_pk_fma_f32 v[146:147], v[2:3], v[210:211], 0 op_sel_hi:[1,1,0]
	v_lshlrev_b32_e32 v156, 16, v157
	v_pk_fma_f32 v[146:147], v[6:7], v[214:215], v[146:147]
	v_and_b32_e32 v157, 0xffff0000, v157
	v_pk_fma_f32 v[146:147], v[10:11], v[220:221], v[146:147]
	v_lshlrev_b32_e32 v160, 16, v161
	v_pk_fma_f32 v[146:147], v[14:15], v[158:159], v[146:147]
	v_and_b32_e32 v161, 0xffff0000, v161
	v_mul_f32_e32 v0, 0xbfb8aa3b, v146
	v_exp_f32_e32 v0, v0
	v_lshlrev_b32_e32 v154, 16, v134
	v_and_b32_e32 v155, 0xffff0000, v134
	v_lshlrev_b32_e32 v158, 16, v142
	v_add_f32_e32 v0, 1.0, v0
	v_rcp_f32_e32 v148, v0
	v_mul_f32_e32 v0, 0xbfb8aa3b, v147
	v_exp_f32_e32 v0, v0
	v_and_b32_e32 v159, 0xffff0000, v142
	v_lshlrev_b32_e32 v134, 16, v135
	v_and_b32_e32 v135, 0xffff0000, v135
	v_add_f32_e32 v0, 1.0, v0
	v_rcp_f32_e32 v149, v0
	v_lshlrev_b32_e32 v142, 16, v143
	v_and_b32_e32 v143, 0xffff0000, v143
	v_pk_mul_f32 v[146:147], v[146:147], v[148:149]
	v_pk_fma_f32 v[148:149], v[4:5], v[152:153], 0 op_sel_hi:[1,1,0]
	v_lshlrev_b32_e32 v152, 16, v133
	v_pk_fma_f32 v[148:149], v[8:9], v[156:157], v[148:149]
	v_and_b32_e32 v153, 0xffff0000, v133
	v_pk_fma_f32 v[148:149], v[12:13], v[222:223], v[148:149]
	v_and_b32_e32 v133, 0xffff0000, v139
	v_pk_fma_f32 v[148:149], v[16:17], v[160:161], v[148:149]
	v_lshlrev_b32_e32 v156, 16, v136
	v_mul_f32_e32 v0, 0xbfb8aa3b, v148
	v_exp_f32_e32 v0, v0
	v_and_b32_e32 v157, 0xffff0000, v136
	v_lshlrev_b32_e32 v160, 16, v144
	v_and_b32_e32 v161, 0xffff0000, v144
	v_add_f32_e32 v0, 1.0, v0
	v_rcp_f32_e32 v150, v0
	v_mul_f32_e32 v0, 0xbfb8aa3b, v149
	v_exp_f32_e32 v0, v0
	v_lshlrev_b32_e32 v136, 16, v137
	v_and_b32_e32 v137, 0xffff0000, v137
	v_lshlrev_b32_e32 v144, 16, v145
	v_add_f32_e32 v0, 1.0, v0
	v_rcp_f32_e32 v151, v0
	v_and_b32_e32 v145, 0xffff0000, v145
	v_pk_mul_f32 v[148:149], v[148:149], v[150:151]
	ds_write_b128 v207, v[146:149] offset:16
	v_lshlrev_b32_e32 v146, 16, v130
	v_and_b32_e32 v147, 0xffff0000, v130
	v_lshlrev_b32_e32 v148, 16, v131
	v_and_b32_e32 v149, 0xffff0000, v131
	v_lshlrev_b32_e32 v130, 16, v138
	v_and_b32_e32 v131, 0xffff0000, v138
	v_pk_fma_f32 v[146:147], v[18:19], v[146:147], 0 op_sel_hi:[1,1,0]
	v_lshlrev_b32_e32 v150, 16, v132
	v_pk_fma_f32 v[130:131], v[30:31], v[130:131], v[146:147]
	v_and_b32_e32 v151, 0xffff0000, v132
	v_pk_fma_f32 v[130:131], v[26:27], v[154:155], v[130:131]
	v_lshlrev_b32_e32 v132, 16, v139
	v_pk_fma_f32 v[130:131], v[22:23], v[158:159], v[130:131]
	v_lshlrev_b32_e32 v138, 16, v140
	v_mul_f32_e32 v0, 0xbfb8aa3b, v130
	v_exp_f32_e32 v0, v0
	v_and_b32_e32 v139, 0xffff0000, v140
	v_lshlrev_b32_e32 v140, 16, v141
	v_and_b32_e32 v141, 0xffff0000, v141
	v_add_f32_e32 v0, 1.0, v0
	v_rcp_f32_e32 v146, v0
	v_mul_f32_e32 v0, 0xbfb8aa3b, v131
	v_exp_f32_e32 v0, v0
	s_nop 0
	v_add_f32_e32 v0, 1.0, v0
	v_rcp_f32_e32 v147, v0
	s_nop 0
	v_pk_mul_f32 v[130:131], v[130:131], v[146:147]
	v_pk_fma_f32 v[146:147], v[20:21], v[148:149], 0 op_sel_hi:[1,1,0]
	s_nop 0
	v_pk_fma_f32 v[132:133], v[32:33], v[132:133], v[146:147]
	s_nop 0
	v_pk_fma_f32 v[132:133], v[28:29], v[134:135], v[132:133]
	s_nop 0
	v_pk_fma_f32 v[132:133], v[24:25], v[142:143], v[132:133]
	v_lshlrev_b32_e32 v142, 16, v126
	v_mul_f32_e32 v0, 0xbfb8aa3b, v132
	v_exp_f32_e32 v0, v0
	v_and_b32_e32 v143, 0xffff0000, v126
	v_lshlrev_b32_e32 v126, 16, v127
	v_and_b32_e32 v127, 0xffff0000, v127
	v_add_f32_e32 v0, 1.0, v0
	v_rcp_f32_e32 v134, v0
	v_mul_f32_e32 v0, 0xbfb8aa3b, v133
	v_exp_f32_e32 v0, v0
	s_nop 0
	v_add_f32_e32 v0, 1.0, v0
; DI float siluf(float x) { return x * __builtin_amdgcn_rcpf(1.f + __expf(-x)); }
; DI void phaseB1(const Params& p, int l, char* smem) {
;     ...
; #pragma unroll
;       for (int i8 = 0; i8 < 8; ++i8) {
;         const int i = (tid >> 5) + 8 * i8;
;         float acc[8];
; #pragma unroll
;         for (int e = 0; e < 8; ++e) acc[e] = 0.f;
; #pragma unroll
;         for (int j = 0; j < 4; ++j) {
;           const uint4 v = rw[i8][j];
;           acc[0] += wv[j][0] * __uint_as_float(v.x << 16); acc[1] += wv[j][1] * __uint_as_float(v.x & 0xffff0000u);
;           acc[2] += wv[j][2] * __uint_as_float(v.y << 16); acc[3] += wv[j][3] * __uint_as_float(v.y & 0xffff0000u);
;           acc[4] += wv[j][4] * __uint_as_float(v.z << 16); acc[5] += wv[j][5] * __uint_as_float(v.z & 0xffff0000u);
;           acc[6] += wv[j][6] * __uint_as_float(v.w << 16); acc[7] += wv[j][7] * __uint_as_float(v.w & 0xffff0000u);
;         }
;         *(float4*)(dstl + i * 132 + c0) = make_float4(siluf(acc[0]), siluf(acc[1]), siluf(acc[2]), siluf(acc[3]));
;         *(float4*)(dstl + i * 132 + c0 + 4) = make_float4(siluf(acc[4]), siluf(acc[5]), siluf(acc[6]), siluf(acc[7]));
;       }
	v_rcp_f32_e32 v135, v0
	s_nop 0
	v_pk_mul_f32 v[132:133], v[132:133], v[134:135]
	ds_write_b128 v207, v[130:133] offset:4224
	v_pk_fma_f32 v[130:131], v[2:3], v[150:151], 0 op_sel_hi:[1,1,0]
	s_nop 0
	v_pk_fma_f32 v[130:131], v[6:7], v[138:139], v[130:131]
	v_lshlrev_b32_e32 v138, 16, v118
	v_pk_fma_f32 v[130:131], v[10:11], v[156:157], v[130:131]
	v_and_b32_e32 v139, 0xffff0000, v118
	v_pk_fma_f32 v[130:131], v[14:15], v[160:161], v[130:131]
	v_lshlrev_b32_e32 v118, 16, v119
	v_mul_f32_e32 v0, 0xbfb8aa3b, v130
	v_exp_f32_e32 v0, v0
	v_and_b32_e32 v119, 0xffff0000, v119
	v_add_f32_e32 v0, 1.0, v0
	v_rcp_f32_e32 v132, v0
	v_mul_f32_e32 v0, 0xbfb8aa3b, v131
	v_exp_f32_e32 v0, v0
	s_nop 0
	v_add_f32_e32 v0, 1.0, v0
	v_rcp_f32_e32 v133, v0
	s_nop 0
	v_pk_mul_f32 v[130:131], v[130:131], v[132:133]
	v_pk_fma_f32 v[132:133], v[4:5], v[152:153], 0 op_sel_hi:[1,1,0]
	s_nop 0
	v_pk_fma_f32 v[132:133], v[8:9], v[140:141], v[132:133]
	v_lshlrev_b32_e32 v140, 16, v120
	v_pk_fma_f32 v[132:133], v[12:13], v[136:137], v[132:133]
	v_lshlrev_b32_e32 v136, 16, v117
	v_pk_fma_f32 v[132:133], v[16:17], v[144:145], v[132:133]
	v_and_b32_e32 v137, 0xffff0000, v117
	v_mul_f32_e32 v0, 0xbfb8aa3b, v132
	v_exp_f32_e32 v0, v0
	v_and_b32_e32 v117, 0xffff0000, v123
	v_and_b32_e32 v141, 0xffff0000, v120
	v_lshlrev_b32_e32 v144, 16, v128
	v_add_f32_e32 v0, 1.0, v0
	v_rcp_f32_e32 v134, v0
	v_mul_f32_e32 v0, 0xbfb8aa3b, v133
	v_exp_f32_e32 v0, v0
	v_and_b32_e32 v145, 0xffff0000, v128
	v_lshlrev_b32_e32 v120, 16, v121
	v_and_b32_e32 v121, 0xffff0000, v121
	v_add_f32_e32 v0, 1.0, v0
	v_rcp_f32_e32 v135, v0
	v_lshlrev_b32_e32 v128, 16, v129
	v_and_b32_e32 v129, 0xffff0000, v129
	v_pk_mul_f32 v[132:133], v[132:133], v[134:135]
	ds_write_b128 v207, v[130:133] offset:4240
	v_lshlrev_b32_e32 v130, 16, v114
	v_and_b32_e32 v131, 0xffff0000, v114
	v_lshlrev_b32_e32 v132, 16, v115
	v_and_b32_e32 v133, 0xffff0000, v115
	v_lshlrev_b32_e32 v114, 16, v122
	v_and_b32_e32 v115, 0xffff0000, v122
	v_pk_fma_f32 v[130:131], v[18:19], v[130:131], 0 op_sel_hi:[1,1,0]
	v_lshlrev_b32_e32 v134, 16, v116
	v_pk_fma_f32 v[114:115], v[30:31], v[114:115], v[130:131]
	v_and_b32_e32 v135, 0xffff0000, v116
	v_pk_fma_f32 v[114:115], v[26:27], v[138:139], v[114:115]
	v_lshlrev_b32_e32 v116, 16, v123
	v_pk_fma_f32 v[114:115], v[22:23], v[142:143], v[114:115]
	v_lshlrev_b32_e32 v122, 16, v124
	v_mul_f32_e32 v0, 0xbfb8aa3b, v114
	v_exp_f32_e32 v0, v0
	v_and_b32_e32 v123, 0xffff0000, v124
	v_lshlrev_b32_e32 v124, 16, v125
	v_and_b32_e32 v125, 0xffff0000, v125
	v_add_f32_e32 v0, 1.0, v0
	v_rcp_f32_e32 v130, v0
	v_mul_f32_e32 v0, 0xbfb8aa3b, v115
	v_exp_f32_e32 v0, v0
	s_nop 0
	v_add_f32_e32 v0, 1.0, v0
	v_rcp_f32_e32 v131, v0
	s_nop 0
	v_pk_mul_f32 v[114:115], v[114:115], v[130:131]
	v_pk_fma_f32 v[130:131], v[20:21], v[132:133], 0 op_sel_hi:[1,1,0]
	s_nop 0
	v_pk_fma_f32 v[116:117], v[32:33], v[116:117], v[130:131]
	s_nop 0
	v_pk_fma_f32 v[116:117], v[28:29], v[118:119], v[116:117]
	s_nop 0
	v_pk_fma_f32 v[116:117], v[24:25], v[126:127], v[116:117]
	v_lshlrev_b32_e32 v126, 16, v110
	v_mul_f32_e32 v0, 0xbfb8aa3b, v116
	v_exp_f32_e32 v0, v0
	v_and_b32_e32 v127, 0xffff0000, v110
	v_lshlrev_b32_e32 v110, 16, v111
	v_and_b32_e32 v111, 0xffff0000, v111
	v_add_f32_e32 v0, 1.0, v0
	v_rcp_f32_e32 v118, v0
	v_mul_f32_e32 v0, 0xbfb8aa3b, v117
	v_exp_f32_e32 v0, v0
	s_nop 0
	v_add_f32_e32 v0, 1.0, v0
	v_rcp_f32_e32 v119, v0
	s_nop 0
	v_pk_mul_f32 v[116:117], v[116:117], v[118:119]
	ds_write_b128 v207, v[114:117] offset:8448
	v_pk_fma_f32 v[114:115], v[2:3], v[134:135], 0 op_sel_hi:[1,1,0]
	s_nop 0
	v_pk_fma_f32 v[114:115], v[6:7], v[122:123], v[114:115]
	v_lshlrev_b32_e32 v122, 16, v102
	v_pk_fma_f32 v[114:115], v[10:11], v[140:141], v[114:115]
	v_and_b32_e32 v123, 0xffff0000, v102
	v_pk_fma_f32 v[114:115], v[14:15], v[144:145], v[114:115]
	v_lshlrev_b32_e32 v102, 16, v103
	v_mul_f32_e32 v0, 0xbfb8aa3b, v114
	v_exp_f32_e32 v0, v0
	v_and_b32_e32 v103, 0xffff0000, v103
	v_add_f32_e32 v0, 1.0, v0
	v_rcp_f32_e32 v116, v0
	v_mul_f32_e32 v0, 0xbfb8aa3b, v115
	v_exp_f32_e32 v0, v0
	s_nop 0
	v_add_f32_e32 v0, 1.0, v0
	v_rcp_f32_e32 v117, v0
	s_nop 0
	v_pk_mul_f32 v[114:115], v[114:115], v[116:117]
	v_pk_fma_f32 v[116:117], v[4:5], v[136:137], 0 op_sel_hi:[1,1,0]
	s_nop 0
	v_pk_fma_f32 v[116:117], v[8:9], v[124:125], v[116:117]
	v_lshlrev_b32_e32 v124, 16, v104
	v_pk_fma_f32 v[116:117], v[12:13], v[120:121], v[116:117]
	v_lshlrev_b32_e32 v120, 16, v101
	v_pk_fma_f32 v[116:117], v[16:17], v[128:129], v[116:117]
	v_and_b32_e32 v121, 0xffff0000, v101
	v_mul_f32_e32 v0, 0xbfb8aa3b, v116
	v_exp_f32_e32 v0, v0
	v_and_b32_e32 v101, 0xffff0000, v107
	v_and_b32_e32 v125, 0xffff0000, v104
	v_lshlrev_b32_e32 v128, 16, v112
	v_add_f32_e32 v0, 1.0, v0
	v_rcp_f32_e32 v118, v0
	v_mul_f32_e32 v0, 0xbfb8aa3b, v117
	v_exp_f32_e32 v0, v0
	v_and_b32_e32 v129, 0xffff0000, v112
	v_lshlrev_b32_e32 v104, 16, v105
	v_and_b32_e32 v105, 0xffff0000, v105
	v_add_f32_e32 v0, 1.0, v0
	v_rcp_f32_e32 v119, v0
	v_lshlrev_b32_e32 v112, 16, v113
	v_and_b32_e32 v113, 0xffff0000, v113
	v_pk_mul_f32 v[116:117], v[116:117], v[118:119]
	ds_write_b128 v207, v[114:117] offset:8464
	v_lshlrev_b32_e32 v114, 16, v98
	v_and_b32_e32 v115, 0xffff0000, v98
	v_lshlrev_b32_e32 v116, 16, v99
	v_and_b32_e32 v117, 0xffff0000, v99
	v_lshlrev_b32_e32 v98, 16, v106
	v_and_b32_e32 v99, 0xffff0000, v106
	v_pk_fma_f32 v[114:115], v[18:19], v[114:115], 0 op_sel_hi:[1,1,0]
	v_lshlrev_b32_e32 v118, 16, v100
	v_pk_fma_f32 v[98:99], v[30:31], v[98:99], v[114:115]
	v_and_b32_e32 v119, 0xffff0000, v100
	v_pk_fma_f32 v[98:99], v[26:27], v[122:123], v[98:99]
	v_lshlrev_b32_e32 v100, 16, v107
; DI float siluf(float x) { return x * __builtin_amdgcn_rcpf(1.f + __expf(-x)); }
; DI void phaseB1(const Params& p, int l, char* smem) {
;     ...
; #pragma unroll
;       for (int i8 = 0; i8 < 8; ++i8) {
;         const int i = (tid >> 5) + 8 * i8;
;         float acc[8];
; #pragma unroll
;         for (int e = 0; e < 8; ++e) acc[e] = 0.f;
; #pragma unroll
;         for (int j = 0; j < 4; ++j) {
;           const uint4 v = rw[i8][j];
;           acc[0] += wv[j][0] * __uint_as_float(v.x << 16); acc[1] += wv[j][1] * __uint_as_float(v.x & 0xffff0000u);
;           acc[2] += wv[j][2] * __uint_as_float(v.y << 16); acc[3] += wv[j][3] * __uint_as_float(v.y & 0xffff0000u);
;           acc[4] += wv[j][4] * __uint_as_float(v.z << 16); acc[5] += wv[j][5] * __uint_as_float(v.z & 0xffff0000u);
;           acc[6] += wv[j][6] * __uint_as_float(v.w << 16); acc[7] += wv[j][7] * __uint_as_float(v.w & 0xffff0000u);
;         }
;         *(float4*)(dstl + i * 132 + c0) = make_float4(siluf(acc[0]), siluf(acc[1]), siluf(acc[2]), siluf(acc[3]));
;         *(float4*)(dstl + i * 132 + c0 + 4) = make_float4(siluf(acc[4]), siluf(acc[5]), siluf(acc[6]), siluf(acc[7]));
;       }
	v_pk_fma_f32 v[98:99], v[22:23], v[126:127], v[98:99]
	v_lshlrev_b32_e32 v106, 16, v108
	v_mul_f32_e32 v0, 0xbfb8aa3b, v98
	v_exp_f32_e32 v0, v0
	v_and_b32_e32 v107, 0xffff0000, v108
	v_lshlrev_b32_e32 v108, 16, v109
	v_and_b32_e32 v109, 0xffff0000, v109
	v_add_f32_e32 v0, 1.0, v0
	v_rcp_f32_e32 v114, v0
	v_mul_f32_e32 v0, 0xbfb8aa3b, v99
	v_exp_f32_e32 v0, v0
	s_nop 0
	v_add_f32_e32 v0, 1.0, v0
	v_rcp_f32_e32 v115, v0
	s_nop 0
	v_pk_mul_f32 v[98:99], v[98:99], v[114:115]
	v_pk_fma_f32 v[114:115], v[20:21], v[116:117], 0 op_sel_hi:[1,1,0]
	s_nop 0
	v_pk_fma_f32 v[100:101], v[32:33], v[100:101], v[114:115]
	s_nop 0
	v_pk_fma_f32 v[100:101], v[28:29], v[102:103], v[100:101]
	s_nop 0
	v_pk_fma_f32 v[100:101], v[24:25], v[110:111], v[100:101]
	v_lshlrev_b32_e32 v110, 16, v94
	v_mul_f32_e32 v0, 0xbfb8aa3b, v100
	v_exp_f32_e32 v0, v0
	v_and_b32_e32 v111, 0xffff0000, v94
	v_lshlrev_b32_e32 v94, 16, v95
	v_and_b32_e32 v95, 0xffff0000, v95
	v_add_f32_e32 v0, 1.0, v0
	v_rcp_f32_e32 v102, v0
	v_mul_f32_e32 v0, 0xbfb8aa3b, v101
	v_exp_f32_e32 v0, v0
	s_nop 0
	v_add_f32_e32 v0, 1.0, v0
	v_rcp_f32_e32 v103, v0
	s_nop 0
	v_pk_mul_f32 v[100:101], v[100:101], v[102:103]
	ds_write_b128 v207, v[98:101] offset:12672
	v_pk_fma_f32 v[98:99], v[2:3], v[118:119], 0 op_sel_hi:[1,1,0]
	s_nop 0
	v_pk_fma_f32 v[98:99], v[6:7], v[106:107], v[98:99]
	v_lshlrev_b32_e32 v106, 16, v86
	v_pk_fma_f32 v[98:99], v[10:11], v[124:125], v[98:99]
	v_and_b32_e32 v107, 0xffff0000, v86
	v_pk_fma_f32 v[98:99], v[14:15], v[128:129], v[98:99]
	v_lshlrev_b32_e32 v86, 16, v87
	v_mul_f32_e32 v0, 0xbfb8aa3b, v98
	v_exp_f32_e32 v0, v0
	v_and_b32_e32 v87, 0xffff0000, v87
	v_add_f32_e32 v0, 1.0, v0
	v_rcp_f32_e32 v100, v0
	v_mul_f32_e32 v0, 0xbfb8aa3b, v99
	v_exp_f32_e32 v0, v0
	s_nop 0
	v_add_f32_e32 v0, 1.0, v0
	v_rcp_f32_e32 v101, v0
	s_nop 0
	v_pk_mul_f32 v[98:99], v[98:99], v[100:101]
	v_pk_fma_f32 v[100:101], v[4:5], v[120:121], 0 op_sel_hi:[1,1,0]
	s_nop 0
	v_pk_fma_f32 v[100:101], v[8:9], v[108:109], v[100:101]
	v_lshlrev_b32_e32 v108, 16, v88
	v_pk_fma_f32 v[100:101], v[12:13], v[104:105], v[100:101]
	v_lshlrev_b32_e32 v104, 16, v85
	v_pk_fma_f32 v[100:101], v[16:17], v[112:113], v[100:101]
	v_and_b32_e32 v105, 0xffff0000, v85
	v_mul_f32_e32 v0, 0xbfb8aa3b, v100
	v_exp_f32_e32 v0, v0
	v_and_b32_e32 v85, 0xffff0000, v91
	v_and_b32_e32 v109, 0xffff0000, v88
	v_lshlrev_b32_e32 v112, 16, v96
	v_add_f32_e32 v0, 1.0, v0
	v_rcp_f32_e32 v102, v0
	v_mul_f32_e32 v0, 0xbfb8aa3b, v101
	v_exp_f32_e32 v0, v0
	v_and_b32_e32 v113, 0xffff0000, v96
	v_lshlrev_b32_e32 v88, 16, v89
	v_and_b32_e32 v89, 0xffff0000, v89
	v_add_f32_e32 v0, 1.0, v0
	v_rcp_f32_e32 v103, v0
	v_lshlrev_b32_e32 v96, 16, v97
	v_and_b32_e32 v97, 0xffff0000, v97
	v_pk_mul_f32 v[100:101], v[100:101], v[102:103]
	ds_write_b128 v207, v[98:101] offset:12688
	v_lshlrev_b32_e32 v98, 16, v82
	v_and_b32_e32 v99, 0xffff0000, v82
	v_lshlrev_b32_e32 v100, 16, v83
	v_and_b32_e32 v101, 0xffff0000, v83
	v_lshlrev_b32_e32 v82, 16, v90
	v_and_b32_e32 v83, 0xffff0000, v90
	v_pk_fma_f32 v[98:99], v[18:19], v[98:99], 0 op_sel_hi:[1,1,0]
	v_lshlrev_b32_e32 v102, 16, v84
	v_pk_fma_f32 v[82:83], v[30:31], v[82:83], v[98:99]
	v_and_b32_e32 v103, 0xffff0000, v84
	v_pk_fma_f32 v[82:83], v[26:27], v[106:107], v[82:83]
	v_lshlrev_b32_e32 v84, 16, v91
	v_pk_fma_f32 v[82:83], v[22:23], v[110:111], v[82:83]
	v_lshlrev_b32_e32 v90, 16, v92
	v_mul_f32_e32 v0, 0xbfb8aa3b, v82
	v_exp_f32_e32 v0, v0
	v_and_b32_e32 v91, 0xffff0000, v92
	v_lshlrev_b32_e32 v92, 16, v93
	v_and_b32_e32 v93, 0xffff0000, v93
	v_add_f32_e32 v0, 1.0, v0
	v_rcp_f32_e32 v98, v0
	v_mul_f32_e32 v0, 0xbfb8aa3b, v83
	v_exp_f32_e32 v0, v0
	s_nop 0
	v_add_f32_e32 v0, 1.0, v0
	v_rcp_f32_e32 v99, v0
	s_nop 0
	v_pk_mul_f32 v[82:83], v[82:83], v[98:99]
	v_pk_fma_f32 v[98:99], v[20:21], v[100:101], 0 op_sel_hi:[1,1,0]
	s_nop 0
	v_pk_fma_f32 v[84:85], v[32:33], v[84:85], v[98:99]
	s_nop 0
	v_pk_fma_f32 v[84:85], v[28:29], v[86:87], v[84:85]
	s_nop 0
	v_pk_fma_f32 v[84:85], v[24:25], v[94:95], v[84:85]
	v_lshlrev_b32_e32 v94, 16, v78
	v_mul_f32_e32 v0, 0xbfb8aa3b, v84
	v_exp_f32_e32 v0, v0
	v_and_b32_e32 v95, 0xffff0000, v78
	v_lshlrev_b32_e32 v78, 16, v79
	v_and_b32_e32 v79, 0xffff0000, v79
	v_add_f32_e32 v0, 1.0, v0
	v_rcp_f32_e32 v86, v0
	v_mul_f32_e32 v0, 0xbfb8aa3b, v85
	v_exp_f32_e32 v0, v0
	s_nop 0
	v_add_f32_e32 v0, 1.0, v0
	v_rcp_f32_e32 v87, v0
	s_nop 0
	v_pk_mul_f32 v[84:85], v[84:85], v[86:87]
	ds_write_b128 v207, v[82:85] offset:16896
	v_pk_fma_f32 v[82:83], v[2:3], v[102:103], 0 op_sel_hi:[1,1,0]
	s_nop 0
	v_pk_fma_f32 v[82:83], v[6:7], v[90:91], v[82:83]
	v_lshlrev_b32_e32 v90, 16, v70
	v_pk_fma_f32 v[82:83], v[10:11], v[108:109], v[82:83]
	v_and_b32_e32 v91, 0xffff0000, v70
	v_pk_fma_f32 v[82:83], v[14:15], v[112:113], v[82:83]
	v_lshlrev_b32_e32 v70, 16, v71
	v_mul_f32_e32 v0, 0xbfb8aa3b, v82
	v_exp_f32_e32 v0, v0
	v_and_b32_e32 v71, 0xffff0000, v71
	v_add_f32_e32 v0, 1.0, v0
	v_rcp_f32_e32 v84, v0
	v_mul_f32_e32 v0, 0xbfb8aa3b, v83
	v_exp_f32_e32 v0, v0
	s_nop 0
	v_add_f32_e32 v0, 1.0, v0
	v_rcp_f32_e32 v85, v0
	s_nop 0
	v_pk_mul_f32 v[82:83], v[82:83], v[84:85]
	v_pk_fma_f32 v[84:85], v[4:5], v[104:105], 0 op_sel_hi:[1,1,0]
	s_nop 0
	v_pk_fma_f32 v[84:85], v[8:9], v[92:93], v[84:85]
	v_lshlrev_b32_e32 v92, 16, v72
	v_pk_fma_f32 v[84:85], v[12:13], v[88:89], v[84:85]
	v_lshlrev_b32_e32 v88, 16, v69
	v_pk_fma_f32 v[84:85], v[16:17], v[96:97], v[84:85]
	v_and_b32_e32 v89, 0xffff0000, v69
	v_mul_f32_e32 v0, 0xbfb8aa3b, v84
	v_exp_f32_e32 v0, v0
	v_and_b32_e32 v69, 0xffff0000, v75
	v_and_b32_e32 v93, 0xffff0000, v72
	v_lshlrev_b32_e32 v96, 16, v80
	v_add_f32_e32 v0, 1.0, v0
	v_rcp_f32_e32 v86, v0
; DI float siluf(float x) { return x * __builtin_amdgcn_rcpf(1.f + __expf(-x)); }
; DI void phaseB1(const Params& p, int l, char* smem) {
;     ...
; #pragma unroll
;       for (int i8 = 0; i8 < 8; ++i8) {
;         const int i = (tid >> 5) + 8 * i8;
;         float acc[8];
; #pragma unroll
;         for (int e = 0; e < 8; ++e) acc[e] = 0.f;
; #pragma unroll
;         for (int j = 0; j < 4; ++j) {
;           const uint4 v = rw[i8][j];
;           acc[0] += wv[j][0] * __uint_as_float(v.x << 16); acc[1] += wv[j][1] * __uint_as_float(v.x & 0xffff0000u);
;           acc[2] += wv[j][2] * __uint_as_float(v.y << 16); acc[3] += wv[j][3] * __uint_as_float(v.y & 0xffff0000u);
;           acc[4] += wv[j][4] * __uint_as_float(v.z << 16); acc[5] += wv[j][5] * __uint_as_float(v.z & 0xffff0000u);
;           acc[6] += wv[j][6] * __uint_as_float(v.w << 16); acc[7] += wv[j][7] * __uint_as_float(v.w & 0xffff0000u);
;         }
;         *(float4*)(dstl + i * 132 + c0) = make_float4(siluf(acc[0]), siluf(acc[1]), siluf(acc[2]), siluf(acc[3]));
;         *(float4*)(dstl + i * 132 + c0 + 4) = make_float4(siluf(acc[4]), siluf(acc[5]), siluf(acc[6]), siluf(acc[7]));
;       }
	v_mul_f32_e32 v0, 0xbfb8aa3b, v85
	v_exp_f32_e32 v0, v0
	v_and_b32_e32 v97, 0xffff0000, v80
	v_lshlrev_b32_e32 v72, 16, v73
	v_and_b32_e32 v73, 0xffff0000, v73
	v_add_f32_e32 v0, 1.0, v0
	v_rcp_f32_e32 v87, v0
	v_lshlrev_b32_e32 v80, 16, v81
	v_and_b32_e32 v81, 0xffff0000, v81
	v_pk_mul_f32 v[84:85], v[84:85], v[86:87]
	ds_write_b128 v207, v[82:85] offset:16912
	v_lshlrev_b32_e32 v82, 16, v66
	v_and_b32_e32 v83, 0xffff0000, v66
	v_lshlrev_b32_e32 v84, 16, v67
	v_and_b32_e32 v85, 0xffff0000, v67
	v_lshlrev_b32_e32 v66, 16, v74
	v_and_b32_e32 v67, 0xffff0000, v74
	v_pk_fma_f32 v[82:83], v[18:19], v[82:83], 0 op_sel_hi:[1,1,0]
	v_lshlrev_b32_e32 v86, 16, v68
	v_pk_fma_f32 v[66:67], v[30:31], v[66:67], v[82:83]
	v_and_b32_e32 v87, 0xffff0000, v68
	v_pk_fma_f32 v[66:67], v[26:27], v[90:91], v[66:67]
	v_lshlrev_b32_e32 v68, 16, v75
	v_pk_fma_f32 v[66:67], v[22:23], v[94:95], v[66:67]
	v_lshlrev_b32_e32 v74, 16, v76
	v_mul_f32_e32 v0, 0xbfb8aa3b, v66
	v_exp_f32_e32 v0, v0
	v_and_b32_e32 v75, 0xffff0000, v76
	v_lshlrev_b32_e32 v76, 16, v77
	v_and_b32_e32 v77, 0xffff0000, v77
	v_add_f32_e32 v0, 1.0, v0
	v_rcp_f32_e32 v82, v0
	v_mul_f32_e32 v0, 0xbfb8aa3b, v67
	v_exp_f32_e32 v0, v0
	s_nop 0
	v_add_f32_e32 v0, 1.0, v0
	v_rcp_f32_e32 v83, v0
	s_nop 0
	v_pk_mul_f32 v[66:67], v[66:67], v[82:83]
	v_pk_fma_f32 v[82:83], v[20:21], v[84:85], 0 op_sel_hi:[1,1,0]
	s_nop 0
	v_pk_fma_f32 v[68:69], v[32:33], v[68:69], v[82:83]
	s_nop 0
	v_pk_fma_f32 v[68:69], v[28:29], v[70:71], v[68:69]
	s_nop 0
	v_pk_fma_f32 v[68:69], v[24:25], v[78:79], v[68:69]
	v_lshlrev_b32_e32 v78, 16, v62
	v_mul_f32_e32 v0, 0xbfb8aa3b, v68
	v_exp_f32_e32 v0, v0
	v_and_b32_e32 v79, 0xffff0000, v62
	v_lshlrev_b32_e32 v62, 16, v63
	v_and_b32_e32 v63, 0xffff0000, v63
	v_add_f32_e32 v0, 1.0, v0
	v_rcp_f32_e32 v70, v0
	v_mul_f32_e32 v0, 0xbfb8aa3b, v69
	v_exp_f32_e32 v0, v0
	s_nop 0
	v_add_f32_e32 v0, 1.0, v0
	v_rcp_f32_e32 v71, v0
	s_nop 0
	v_pk_mul_f32 v[68:69], v[68:69], v[70:71]
	ds_write_b128 v207, v[66:69] offset:21120
	v_pk_fma_f32 v[66:67], v[2:3], v[86:87], 0 op_sel_hi:[1,1,0]
	s_nop 0
	v_pk_fma_f32 v[66:67], v[6:7], v[74:75], v[66:67]
	v_lshlrev_b32_e32 v74, 16, v54
	v_pk_fma_f32 v[66:67], v[10:11], v[92:93], v[66:67]
	v_and_b32_e32 v75, 0xffff0000, v54
	v_pk_fma_f32 v[66:67], v[14:15], v[96:97], v[66:67]
	v_lshlrev_b32_e32 v54, 16, v55
	v_mul_f32_e32 v0, 0xbfb8aa3b, v66
	v_exp_f32_e32 v0, v0
	v_and_b32_e32 v55, 0xffff0000, v55
	v_add_f32_e32 v0, 1.0, v0
	v_rcp_f32_e32 v68, v0
	v_mul_f32_e32 v0, 0xbfb8aa3b, v67
	v_exp_f32_e32 v0, v0
	s_nop 0
	v_add_f32_e32 v0, 1.0, v0
	v_rcp_f32_e32 v69, v0
	s_nop 0
	v_pk_mul_f32 v[66:67], v[66:67], v[68:69]
	v_pk_fma_f32 v[68:69], v[4:5], v[88:89], 0 op_sel_hi:[1,1,0]
	s_nop 0
	v_pk_fma_f32 v[68:69], v[8:9], v[76:77], v[68:69]
	v_lshlrev_b32_e32 v76, 16, v56
	v_pk_fma_f32 v[68:69], v[12:13], v[72:73], v[68:69]
	v_lshlrev_b32_e32 v72, 16, v53
	v_pk_fma_f32 v[68:69], v[16:17], v[80:81], v[68:69]
	v_and_b32_e32 v73, 0xffff0000, v53
	v_mul_f32_e32 v0, 0xbfb8aa3b, v68
	v_exp_f32_e32 v0, v0
	v_and_b32_e32 v53, 0xffff0000, v59
	v_and_b32_e32 v77, 0xffff0000, v56
	v_lshlrev_b32_e32 v80, 16, v64
	v_add_f32_e32 v0, 1.0, v0
	v_rcp_f32_e32 v70, v0
	v_mul_f32_e32 v0, 0xbfb8aa3b, v69
	v_exp_f32_e32 v0, v0
	v_and_b32_e32 v81, 0xffff0000, v64
	v_lshlrev_b32_e32 v56, 16, v57
	v_and_b32_e32 v57, 0xffff0000, v57
	v_add_f32_e32 v0, 1.0, v0
	v_rcp_f32_e32 v71, v0
	v_lshlrev_b32_e32 v64, 16, v65
	v_and_b32_e32 v65, 0xffff0000, v65
	v_pk_mul_f32 v[68:69], v[68:69], v[70:71]
	ds_write_b128 v207, v[66:69] offset:21136
	v_lshlrev_b32_e32 v66, 16, v50
	v_and_b32_e32 v67, 0xffff0000, v50
	v_lshlrev_b32_e32 v68, 16, v51
	v_and_b32_e32 v69, 0xffff0000, v51
	v_lshlrev_b32_e32 v50, 16, v58
	v_and_b32_e32 v51, 0xffff0000, v58
	v_pk_fma_f32 v[66:67], v[18:19], v[66:67], 0 op_sel_hi:[1,1,0]
	v_lshlrev_b32_e32 v70, 16, v52
	v_pk_fma_f32 v[50:51], v[30:31], v[50:51], v[66:67]
	v_and_b32_e32 v71, 0xffff0000, v52
	v_pk_fma_f32 v[50:51], v[26:27], v[74:75], v[50:51]
	v_lshlrev_b32_e32 v52, 16, v59
	v_pk_fma_f32 v[50:51], v[22:23], v[78:79], v[50:51]
	v_lshlrev_b32_e32 v58, 16, v60
	v_mul_f32_e32 v0, 0xbfb8aa3b, v50
	v_exp_f32_e32 v0, v0
	v_and_b32_e32 v59, 0xffff0000, v60
	v_lshlrev_b32_e32 v60, 16, v61
	v_and_b32_e32 v61, 0xffff0000, v61
	v_add_f32_e32 v0, 1.0, v0
	v_rcp_f32_e32 v66, v0
	v_mul_f32_e32 v0, 0xbfb8aa3b, v51
	v_exp_f32_e32 v0, v0
	s_nop 0
	v_add_f32_e32 v0, 1.0, v0
	v_rcp_f32_e32 v67, v0
	s_nop 0
	v_pk_mul_f32 v[50:51], v[50:51], v[66:67]
	v_pk_fma_f32 v[66:67], v[20:21], v[68:69], 0 op_sel_hi:[1,1,0]
	s_nop 0
	v_pk_fma_f32 v[52:53], v[32:33], v[52:53], v[66:67]
	s_nop 0
	v_pk_fma_f32 v[52:53], v[28:29], v[54:55], v[52:53]
	s_nop 0
	v_pk_fma_f32 v[52:53], v[24:25], v[62:63], v[52:53]
	v_lshlrev_b32_e32 v62, 16, v46
	v_mul_f32_e32 v0, 0xbfb8aa3b, v52
	v_exp_f32_e32 v0, v0
	v_and_b32_e32 v63, 0xffff0000, v46
	v_lshlrev_b32_e32 v46, 16, v47
	v_and_b32_e32 v47, 0xffff0000, v47
	v_add_f32_e32 v0, 1.0, v0
	v_rcp_f32_e32 v54, v0
	v_mul_f32_e32 v0, 0xbfb8aa3b, v53
	v_exp_f32_e32 v0, v0
	s_nop 0
	v_add_f32_e32 v0, 1.0, v0
	v_rcp_f32_e32 v55, v0
	s_nop 0
	v_pk_mul_f32 v[52:53], v[52:53], v[54:55]
	ds_write_b128 v207, v[50:53] offset:25344
	v_pk_fma_f32 v[50:51], v[2:3], v[70:71], 0 op_sel_hi:[1,1,0]
	s_nop 0
	v_pk_fma_f32 v[50:51], v[6:7], v[58:59], v[50:51]
	v_lshlrev_b32_e32 v58, 16, v38
	v_pk_fma_f32 v[50:51], v[10:11], v[76:77], v[50:51]
	v_and_b32_e32 v59, 0xffff0000, v38
	v_pk_fma_f32 v[50:51], v[14:15], v[80:81], v[50:51]
	v_lshlrev_b32_e32 v38, 16, v39
	v_mul_f32_e32 v0, 0xbfb8aa3b, v50
	v_exp_f32_e32 v0, v0
	v_and_b32_e32 v39, 0xffff0000, v39
	v_add_f32_e32 v0, 1.0, v0
; DI float siluf(float x) { return x * __builtin_amdgcn_rcpf(1.f + __expf(-x)); }
; DI void phaseB1(const Params& p, int l, char* smem) {
;     ...
;         *(float4*)(dstl + i * 132 + c0) = make_float4(siluf(acc[0]), siluf(acc[1]), siluf(acc[2]), siluf(acc[3]));
;         *(float4*)(dstl + i * 132 + c0 + 4) = make_float4(siluf(acc[4]), siluf(acc[5]), siluf(acc[6]), siluf(acc[7]));
;       }
;     }
;     __syncthreads();
;     if (tid < 128) {
;       const int row = tid & 63, which = tid >> 6;
;       const float* src = which ? ks : qs;
;       float ss = 0.f;
;       for (int c0 = 0; c0 < 128; ++c0) { const int c = (c0 + row) & 127; const float v = src[row * 132 + c]; ss += v * v; }
;       float rr = rsqrtf(ss + 1e-6f);
;       if (which) rk[row] = rr; else rq[row] = rr * 0.08838834764831845f;
;     } else if (tid < 192) {
;       const int i = tid - 128;
;       const float a = p.small[(size_t)(tok0 + i) * 32 + 8 + hd];
;       const float bb = p.small[(size_t)(tok0 + i) * 32 + 12 + hd];
;       const float xx = a + p.b_dt_bias[l * 4 + hd];
;       const float ex = __expf(xx);
;       const float sp = xx > 20.f ? xx : (ex < 0.01f ? ex * (1.f - ex * (0.5f - ex * (1.f / 3.f))) : __logf(1.f + ex));
;       float g = -__expf(p.b_a_log[l * 4 + hd]) * sp;
	v_rcp_f32_e32 v52, v0
	v_mul_f32_e32 v0, 0xbfb8aa3b, v51
	v_exp_f32_e32 v0, v0
	s_nop 0
	v_add_f32_e32 v0, 1.0, v0
	v_rcp_f32_e32 v53, v0
	s_nop 0
	v_pk_mul_f32 v[50:51], v[50:51], v[52:53]
	v_pk_fma_f32 v[52:53], v[4:5], v[72:73], 0 op_sel_hi:[1,1,0]
	s_nop 0
	v_pk_fma_f32 v[52:53], v[8:9], v[60:61], v[52:53]
	v_lshlrev_b32_e32 v60, 16, v40
	v_pk_fma_f32 v[52:53], v[12:13], v[56:57], v[52:53]
	v_lshlrev_b32_e32 v56, 16, v44
	v_pk_fma_f32 v[52:53], v[16:17], v[64:65], v[52:53]
	v_and_b32_e32 v57, 0xffff0000, v44
	v_mul_f32_e32 v0, 0xbfb8aa3b, v52
	v_exp_f32_e32 v0, v0
	v_and_b32_e32 v61, 0xffff0000, v40
	v_lshlrev_b32_e32 v64, 16, v48
	v_and_b32_e32 v65, 0xffff0000, v48
	v_add_f32_e32 v0, 1.0, v0
	v_rcp_f32_e32 v54, v0
	v_mul_f32_e32 v0, 0xbfb8aa3b, v53
	v_exp_f32_e32 v0, v0
	v_lshlrev_b32_e32 v44, 16, v45
	v_and_b32_e32 v45, 0xffff0000, v45
	v_lshlrev_b32_e32 v40, 16, v41
	v_add_f32_e32 v0, 1.0, v0
	v_rcp_f32_e32 v55, v0
	v_and_b32_e32 v41, 0xffff0000, v41
	v_lshlrev_b32_e32 v48, 16, v49
	v_and_b32_e32 v49, 0xffff0000, v49
	v_pk_mul_f32 v[52:53], v[52:53], v[54:55]
	ds_write_b128 v207, v[50:53] offset:25360
	v_lshlrev_b32_e32 v50, 16, v34
	v_and_b32_e32 v51, 0xffff0000, v34
	v_lshlrev_b32_e32 v54, 16, v42
	v_and_b32_e32 v55, 0xffff0000, v42
	v_pk_fma_f32 v[18:19], v[18:19], v[50:51], 0 op_sel_hi:[1,1,0]
	v_lshlrev_b32_e32 v34, 16, v35
	v_pk_fma_f32 v[18:19], v[30:31], v[54:55], v[18:19]
	v_and_b32_e32 v35, 0xffff0000, v35
	v_pk_fma_f32 v[18:19], v[26:27], v[58:59], v[18:19]
	v_lshlrev_b32_e32 v42, 16, v43
	v_pk_fma_f32 v[18:19], v[22:23], v[62:63], v[18:19]
	v_and_b32_e32 v43, 0xffff0000, v43
	v_mul_f32_e32 v0, 0xbfb8aa3b, v18
	v_exp_f32_e32 v0, v0
	v_pk_fma_f32 v[20:21], v[20:21], v[34:35], 0 op_sel_hi:[1,1,0]
	v_lshlrev_b32_e32 v52, 16, v36
	v_pk_fma_f32 v[20:21], v[32:33], v[42:43], v[20:21]
	v_add_f32_e32 v0, 1.0, v0
	v_rcp_f32_e32 v22, v0
	v_mul_f32_e32 v0, 0xbfb8aa3b, v19
	v_exp_f32_e32 v0, v0
	v_pk_fma_f32 v[20:21], v[28:29], v[38:39], v[20:21]
	v_and_b32_e32 v53, 0xffff0000, v36
	v_pk_fma_f32 v[20:21], v[24:25], v[46:47], v[20:21]
	v_add_f32_e32 v0, 1.0, v0
	v_rcp_f32_e32 v23, v0
	v_mul_f32_e32 v0, 0xbfb8aa3b, v20
	v_exp_f32_e32 v0, v0
	v_pk_fma_f32 v[2:3], v[2:3], v[52:53], 0 op_sel_hi:[1,1,0]
	v_pk_mul_f32 v[18:19], v[18:19], v[22:23]
	v_pk_fma_f32 v[2:3], v[6:7], v[56:57], v[2:3]
	v_add_f32_e32 v0, 1.0, v0
	v_rcp_f32_e32 v22, v0
	v_mul_f32_e32 v0, 0xbfb8aa3b, v21
	v_exp_f32_e32 v0, v0
	v_pk_fma_f32 v[2:3], v[10:11], v[60:61], v[2:3]
	v_lshlrev_b32_e32 v36, 16, v37
	v_pk_fma_f32 v[2:3], v[14:15], v[64:65], v[2:3]
	v_add_f32_e32 v0, 1.0, v0
	v_rcp_f32_e32 v23, v0
	v_mul_f32_e32 v0, 0xbfb8aa3b, v2
	v_exp_f32_e32 v0, v0
	v_and_b32_e32 v37, 0xffff0000, v37
	v_pk_fma_f32 v[4:5], v[4:5], v[36:37], 0 op_sel_hi:[1,1,0]
	v_pk_mul_f32 v[20:21], v[20:21], v[22:23]
	v_add_f32_e32 v0, 1.0, v0
	v_rcp_f32_e32 v6, v0
	v_mul_f32_e32 v0, 0xbfb8aa3b, v3
	v_exp_f32_e32 v0, v0
	v_pk_fma_f32 v[4:5], v[8:9], v[44:45], v[4:5]
	ds_write_b128 v207, v[18:21] offset:29568
	v_pk_fma_f32 v[4:5], v[12:13], v[40:41], v[4:5]
	v_add_f32_e32 v0, 1.0, v0
	v_pk_fma_f32 v[4:5], v[16:17], v[48:49], v[4:5]
	v_rcp_f32_e32 v7, v0
	v_mul_f32_e32 v0, 0xbfb8aa3b, v4
	v_exp_f32_e32 v0, v0
	v_pk_mul_f32 v[2:3], v[2:3], v[6:7]
	v_add_f32_e32 v0, 1.0, v0
	v_rcp_f32_e32 v6, v0
	v_mul_f32_e32 v0, 0xbfb8aa3b, v5
	v_exp_f32_e32 v0, v0
	s_nop 0
	v_add_f32_e32 v0, 1.0, v0
	v_rcp_f32_e32 v7, v0
	s_nop 0
	v_pk_mul_f32 v[4:5], v[4:5], v[6:7]
	ds_write_b128 v207, v[2:5] offset:29584
	s_waitcnt lgkmcnt(0)
	s_barrier
	s_and_saveexec_b64 s[8:9], s[4:5]
	s_xor_b64 s[68:69], exec, s[8:9]
	s_cbranch_execz .LBB0_1855
	s_and_saveexec_b64 s[70:71], s[60:61]
	s_cbranch_execz .LBB0_1854
	v_add_u32_e32 v2, s35, v177
	v_ashrrev_i32_e32 v3, 31, v2
	v_readlane_b32 s16, v252, 57
	v_lshlrev_b64 v[2:3], 7, v[2:3]
	v_readlane_b32 s17, v252, 58
	v_readlane_b32 s18, v252, 59
	v_readlane_b32 s19, v252, 60
	v_readlane_b32 s20, v252, 61
	v_readlane_b32 s21, v252, 62
	v_readlane_b32 s22, v252, 63
	v_readlane_b32 s23, v253, 0
	v_readlane_b32 s24, v253, 1
	v_readlane_b32 s25, v253, 2
	v_readlane_b32 s26, v253, 3
	v_readlane_b32 s27, v253, 4
	v_readlane_b32 s28, v253, 5
	v_readlane_b32 s29, v253, 6
	v_readlane_b32 s30, v253, 7
	v_readlane_b32 s31, v253, 8
	s_or_b32 s8, s3, s36
	s_ashr_i32 s9, s8, 31
	v_lshl_add_u64 v[2:3], s[30:31], 0, v[2:3]
	v_readlane_b32 s16, v250, 18
	s_lshl_b32 s14, s3, 2
	s_lshl_b64 s[72:73], s[8:9], 2
	v_readlane_b32 s18, v250, 20
	v_readlane_b32 s19, v250, 21
	s_add_u32 s8, s18, s72
	v_lshl_add_u64 v[2:3], v[2:3], 0, s[14:15]
	s_addc_u32 s9, s19, s73
	global_load_dword v4, v[2:3], off offset:32
	global_load_dword v0, v[2:3], off offset:48
	s_mov_b32 s3, 0x41a00000
	global_load_dword v2, v1, s[8:9]
	v_readlane_b32 s17, v250, 19
	s_add_u32 s8, s16, s72
	s_addc_u32 s9, s17, s73
	global_load_dword v5, v1, s[8:9]
	v_readlane_b32 s20, v250, 22
	v_readlane_b32 s21, v250, 23
	v_readlane_b32 s22, v250, 24
	v_readlane_b32 s23, v250, 25
	v_readlane_b32 s24, v250, 26
	v_readlane_b32 s25, v250, 27
	v_readlane_b32 s26, v250, 28
	v_readlane_b32 s27, v250, 29
	v_readlane_b32 s28, v250, 30
	v_readlane_b32 s29, v250, 31
	v_readlane_b32 s30, v250, 32
	v_readlane_b32 s31, v250, 33
	s_waitcnt vmcnt(0)
	v_add_f32_e32 v2, v4, v2
	v_cmp_nlt_f32_e32 vcc, s3, v2
	s_and_saveexec_b64 s[74:75], vcc
	s_cbranch_execz .LBB0_1853
	v_mul_f32_e32 v2, 0x3fb8aa3b, v2
	v_exp_f32_e32 v3, v2
	s_mov_b32 s3, 0x3c23d70a
	v_cmp_ngt_f32_e32 vcc, s3, v3
	s_and_saveexec_b64 s[8:9], vcc
	s_xor_b64 s[8:9], exec, s[8:9]
	s_cbranch_execz .LBB0_1850
	v_add_f32_e32 v2, 1.0, v3
	s_mov_b32 s3, 0x800000
	v_cmp_gt_f32_e64 s[88:89], s3, v2
	s_mov_b32 s3, 0x3f317217
	s_nop 0
	v_cndmask_b32_e64 v3, 0, 32, s[88:89]
	v_ldexp_f32 v2, v2, v3
	v_log_f32_e32 v2, v2
	s_nop 0
	v_mul_f32_e32 v3, 0x3f317217, v2
	v_fma_f32 v3, v2, s3, -v3
	v_fmac_f32_e32 v3, 0x3377d1cf, v2
	s_mov_b32 s3, 0x7f800000
	v_fmac_f32_e32 v3, 0x3f317217, v2
	v_cmp_lt_f32_e64 vcc, |v2|, s3
	s_nop 1
	v_cndmask_b32_e32 v2, v2, v3, vcc
	v_mov_b32_e32 v3, 0x41b17218
	v_cndmask_b32_e64 v3, 0, v3, s[88:89]
	v_sub_f32_e32 v2, v2, v3

; DI float sigmoidf(float x) { return __builtin_amdgcn_rcpf(1.f + __expf(-x)); }
; DI void phaseB1(const Params& p, int l, char* smem) {
;     ...
;       const float xx = a + p.b_dt_bias[l * 4 + hd];
;       const float ex = __expf(xx);
;       const float sp = xx > 20.f ? xx : (ex < 0.01f ? ex * (1.f - ex * (0.5f - ex * (1.f / 3.f))) : __logf(1.f + ex));
;       float g = -__expf(p.b_a_log[l * 4 + hd]) * sp;
; #pragma unroll
;       for (int o = 1; o < 64; o <<= 1) { const float v = __shfl_up(g, o); if (lane >= o) g += v; }
;       gcum[i] = g; beta[i] = sigmoidf(bb); eg[i] = __expf(g);
.LBB0_1853:
	s_or_b64 exec, exec, s[74:75]
	v_readlane_b32 s16, v250, 18
	v_readlane_b32 s17, v250, 19
	v_mov_b32_e32 v3, v5
	v_and_b32_e32 v5, 64, v249
	v_add_u32_e32 v6, -1, v249
	v_cmp_lt_i32_e32 vcc, v6, v5
	v_readlane_b32 s8, v255, 4
	v_readlane_b32 s9, v255, 5
	v_cndmask_b32_e32 v6, v6, v249, vcc
	v_lshlrev_b32_e32 v6, 2, v6
	v_mul_f32_e32 v0, 0xbfb8aa3b, v0
	v_exp_f32_e32 v0, v0
	v_readlane_b32 s18, v250, 20
	v_readlane_b32 s19, v250, 21
	v_readlane_b32 s20, v250, 22
	v_add_f32_e32 v0, 1.0, v0
	v_rcp_f32_e32 v0, v0
	v_readlane_b32 s21, v250, 23
	v_readlane_b32 s22, v250, 24
	v_readlane_b32 s23, v250, 25
	ds_write_b32 v179, v0
	v_readlane_b32 s24, v250, 26
	v_readlane_b32 s25, v250, 27
	v_readlane_b32 s26, v250, 28
	v_readlane_b32 s27, v250, 29
	v_readlane_b32 s28, v250, 30
	v_readlane_b32 s29, v250, 31
	v_readlane_b32 s30, v250, 32
	v_readlane_b32 s31, v250, 33
	s_waitcnt vmcnt(0)
	v_mul_f32_e32 v3, 0x3fb8aa3b, v3
	v_exp_f32_e32 v3, v3
	s_nop 0
	v_mul_f32_e64 v4, v2, -v3
	ds_bpermute_b32 v6, v6, v4
	s_waitcnt lgkmcnt(0)
	v_fma_f32 v2, v2, -v3, v6
	v_add_u32_e32 v3, -2, v249
	v_cmp_lt_i32_e32 vcc, v3, v5
	v_cndmask_b32_e64 v2, v2, v4, s[8:9]
	v_readlane_b32 s8, v255, 6
	v_cndmask_b32_e32 v3, v3, v249, vcc
	v_lshlrev_b32_e32 v3, 2, v3
	ds_bpermute_b32 v3, v3, v2
	v_readlane_b32 s9, v255, 7
	s_waitcnt lgkmcnt(0)
	v_add_f32_e32 v3, v2, v3
	v_cndmask_b32_e64 v2, v3, v2, s[8:9]
	v_add_u32_e32 v3, -4, v249
	v_cmp_lt_i32_e32 vcc, v3, v5
	v_readlane_b32 s8, v255, 8
	v_readlane_b32 s9, v255, 9
	v_cndmask_b32_e32 v3, v3, v249, vcc
	v_lshlrev_b32_e32 v3, 2, v3
	ds_bpermute_b32 v3, v3, v2
	s_waitcnt lgkmcnt(0)
	v_add_f32_e32 v3, v2, v3
	v_cndmask_b32_e64 v2, v3, v2, s[8:9]
	v_add_u32_e32 v3, -8, v249
	v_cmp_lt_i32_e32 vcc, v3, v5
	v_readlane_b32 s8, v255, 10
	v_readlane_b32 s9, v255, 11
	v_cndmask_b32_e32 v3, v3, v249, vcc
	v_lshlrev_b32_e32 v3, 2, v3
	ds_bpermute_b32 v3, v3, v2
	s_waitcnt lgkmcnt(0)
	v_add_f32_e32 v3, v2, v3
	v_cndmask_b32_e64 v2, v3, v2, s[8:9]
	v_add_u32_e32 v3, -16, v249
	v_cmp_lt_i32_e32 vcc, v3, v5
	v_readlane_b32 s8, v255, 12
	v_readlane_b32 s9, v255, 13
	v_cndmask_b32_e32 v3, v3, v249, vcc
	v_lshlrev_b32_e32 v3, 2, v3
	ds_bpermute_b32 v3, v3, v2
	s_waitcnt lgkmcnt(0)
	v_add_f32_e32 v3, v2, v3
	v_cndmask_b32_e64 v2, v3, v2, s[8:9]
	v_subrev_u32_e32 v3, 32, v249
	v_cmp_lt_i32_e32 vcc, v3, v5
	v_readlane_b32 s8, v255, 14
	v_readlane_b32 s9, v255, 15
	v_cndmask_b32_e32 v3, v3, v249, vcc
	v_lshlrev_b32_e32 v3, 2, v3
	ds_bpermute_b32 v3, v3, v2
	s_waitcnt lgkmcnt(0)
	v_add_f32_e32 v3, v2, v3
	v_cndmask_b32_e64 v2, v3, v2, s[8:9]
	v_mul_f32_e32 v0, 0x3fb8aa3b, v2
	v_exp_f32_e32 v0, v0
	ds_write_b32 v178, v2
	ds_write_b32 v180, v0
